# HGRN input GEMM epilogue: the 8 ssq loads issued together with counted waits
# speedup vs baseline: 1.0839x; 1.0027x over previous
; __device__ __forceinline__ float silu_(float v) { return v * __builtin_amdgcn_rcpf(1.0f + __expf(-v)); }
;     __device__ __forceinline__ void operator()(const f32x4 (&acc)[2][2][4][2], const Unit& u, int wr, int wc, int fr, int fq) const {
;     ...
;             for (int m = 0; m < 4; ++m) { const int row = u.pm * 256 + ai * 128 + wr * 64 + m * 16 + fr; const float rs = rsqrtf(ssq[row] * (1.0f / 1024.0f) + NEPS);
; #pragma unroll
;                 for (int bj = 0; bj < 2; ++bj) { f32x4 v0 = acc[ai][bj][m][0] * rs, v1 = acc[ai][bj][m][1] * rs;
;                     if (act) {
; #pragma unroll
;                         for (int e = 0; e < 4; ++e) { v0[e] = silu_(v0[e]); v1[e] = silu_(v1[e]); } }
.LBB0_716:
	s_ashr_i32 s13, s2, 2
	s_cmp_lt_u32 s2, 4
	s_cselect_b64 s[38:39], -1, 0
	s_cmp_eq_u32 s13, 4
	s_cselect_b64 s[40:41], -1, 0
	s_lshl_b32 s12, s63, 8
	v_add_u32_e32 v142, s12, v152
	v_add_u32_e32 v240, s12, v152
	v_ashrrev_i32_e32 v241, 31, v240
	v_lshl_add_u64 v[240:241], v[240:241], 2, s[0:1]
	global_load_dword v244, v[240:241], off
	v_add_u32_e32 v240, s12, v154
	v_ashrrev_i32_e32 v241, 31, v240
	v_lshl_add_u64 v[240:241], v[240:241], 2, s[0:1]
	global_load_dword v245, v[240:241], off
	v_add_u32_e32 v240, s12, v155
	v_ashrrev_i32_e32 v241, 31, v240
	v_lshl_add_u64 v[240:241], v[240:241], 2, s[0:1]
	global_load_dword v246, v[240:241], off
	v_add_u32_e32 v240, s12, v156
	v_ashrrev_i32_e32 v241, 31, v240
	v_lshl_add_u64 v[240:241], v[240:241], 2, s[0:1]
	global_load_dword v247, v[240:241], off
	v_add_u32_e32 v240, 0x80, v142
	v_ashrrev_i32_e32 v241, 31, v240
	v_lshl_add_u64 v[240:241], v[240:241], 2, s[0:1]
	global_load_dword v248, v[240:241], off
	v_add_u32_e32 v240, 0x90, v142
	v_ashrrev_i32_e32 v241, 31, v240
	v_lshl_add_u64 v[240:241], v[240:241], 2, s[0:1]
	global_load_dword v249, v[240:241], off
	v_add_u32_e32 v240, 0xa0, v142
	v_ashrrev_i32_e32 v241, 31, v240
	v_lshl_add_u64 v[240:241], v[240:241], 2, s[0:1]
	global_load_dword v250, v[240:241], off
	v_add_u32_e32 v240, 0xb0, v142
	v_ashrrev_i32_e32 v241, 31, v240
	v_lshl_add_u64 v[240:241], v[240:241], 2, s[0:1]
	global_load_dword v251, v[240:241], off
	v_ashrrev_i32_e32 v143, 31, v142
	v_lshl_add_u64 v[144:145], v[142:143], 2, s[0:1]
	s_waitcnt vmcnt(7)
	v_mov_b32_e32 v0, v244
	s_or_b64 s[40:41], s[38:39], s[40:41]
	v_fmamk_f32 v0, v0, 0x3a800000, v196
	v_cmp_gt_f32_e32 vcc, s33, v0
	v_mul_f32_e32 v144, 0x4b800000, v0
	s_nop 0
	v_cndmask_b32_e32 v0, v0, v144, vcc
	v_rsq_f32_e32 v0, v0
	s_nop 0
	v_mul_f32_e32 v144, 0x45800000, v0
	v_cndmask_b32_e32 v144, v0, v144, vcc
	v_cndmask_b32_e64 v0, 0, 1, s[40:41]
	v_pk_mul_f32 v[148:149], v[124:125], v[144:145] op_sel_hi:[1,0]
	v_pk_mul_f32 v[150:151], v[122:123], v[144:145] op_sel_hi:[1,0]
	v_pk_mul_f32 v[124:125], v[128:129], v[144:145] op_sel_hi:[1,0]
	v_pk_mul_f32 v[126:127], v[126:127], v[144:145] op_sel_hi:[1,0]
	v_cmp_ne_u32_e64 s[38:39], 1, v0
	s_andn2_b64 vcc, exec, s[40:41]
	s_cbranch_vccnz .LBB0_718
	v_mul_f32_e32 v0, 0xbfb8aa3b, v150
	v_exp_f32_e32 v0, v0
	s_nop 0
	v_add_f32_e32 v0, 1.0, v0
	v_rcp_f32_e32 v122, v0
	v_mul_f32_e32 v0, 0xbfb8aa3b, v126
	v_exp_f32_e32 v0, v0
	s_nop 0
	v_add_f32_e32 v0, 1.0, v0
	v_rcp_f32_e32 v128, v0
	v_mul_f32_e32 v0, 0xbfb8aa3b, v151
	v_exp_f32_e32 v0, v0
	s_nop 0
	v_add_f32_e32 v0, 1.0, v0
	v_rcp_f32_e32 v123, v0
	v_mul_f32_e32 v0, 0xbfb8aa3b, v127
	v_exp_f32_e32 v0, v0
	v_pk_mul_f32 v[150:151], v[150:151], v[122:123]
	v_add_f32_e32 v0, 1.0, v0
	v_rcp_f32_e32 v129, v0
	v_mul_f32_e32 v0, 0xbfb8aa3b, v148
	v_exp_f32_e32 v0, v0
	v_pk_mul_f32 v[126:127], v[126:127], v[128:129]
	v_add_f32_e32 v0, 1.0, v0
	v_rcp_f32_e32 v146, v0
	v_mul_f32_e32 v0, 0xbfb8aa3b, v124
	v_exp_f32_e32 v0, v0
	s_nop 0
	v_add_f32_e32 v0, 1.0, v0
	v_rcp_f32_e32 v160, v0
	v_mul_f32_e32 v0, 0xbfb8aa3b, v149
	v_exp_f32_e32 v0, v0
	s_nop 0
	v_add_f32_e32 v0, 1.0, v0
	v_rcp_f32_e32 v147, v0
	v_mul_f32_e32 v0, 0xbfb8aa3b, v125
	v_exp_f32_e32 v0, v0
	v_pk_mul_f32 v[148:149], v[148:149], v[146:147]
	v_add_f32_e32 v0, 1.0, v0
	v_rcp_f32_e32 v161, v0
	s_nop 0
	v_pk_mul_f32 v[124:125], v[124:125], v[160:161]

; __device__ __forceinline__ u32x4 pack8(const f32x4 a, const f32x4 b) { u32x4 w; w.x = cvt_pk_bf16(a[0], a[1]); w.y = cvt_pk_bf16(a[2], a[3]); w.z = cvt_pk_bf16(b[0], b[1]); w.w = cvt_pk_bf16(b[2], b[3]); return w; }
; __device__ __forceinline__ float silu_(float v) { return v * __builtin_amdgcn_rcpf(1.0f + __expf(-v)); }
;     __device__ __forceinline__ void operator()(const f32x4 (&acc)[2][2][4][2], const Unit& u, int wr, int wc, int fr, int fq) const {
;     ...
;             for (int m = 0; m < 4; ++m) { const int row = u.pm * 256 + ai * 128 + wr * 64 + m * 16 + fr; const float rs = rsqrtf(ssq[row] * (1.0f / 1024.0f) + NEPS);
; #pragma unroll
;                 for (int bj = 0; bj < 2; ++bj) { f32x4 v0 = acc[ai][bj][m][0] * rs, v1 = acc[ai][bj][m][1] * rs;
;                     if (act) {
; #pragma unroll
;                         for (int e = 0; e < 4; ++e) { v0[e] = silu_(v0[e]); v1[e] = silu_(v1[e]); } }
;                     *(u32x4*)(dst + (size_t)row * 1024 + colt + bj * 128) = pack8(v0, v1); } }
.LBB0_720:
	v_cvt_pk_bf16_f32 v118, v118, v119
	v_cvt_pk_bf16_f32 v119, v120, v121
	v_cvt_pk_bf16_f32 v120, v114, v115
	v_add_u32_e32 v114, s12, v154
	v_cvt_pk_bf16_f32 v121, v116, v117
	v_ashrrev_i32_e32 v115, 31, v114
	global_store_dwordx4 v[128:129], v[118:121], off offset:256
	v_lshl_add_u64 v[116:117], v[114:115], 2, s[0:1]
	s_waitcnt vmcnt(8)
	v_mov_b32_e32 v0, v245
	s_and_b64 vcc, exec, s[38:39]
	v_fmamk_f32 v0, v0, 0x3a800000, v196
	v_mul_f32_e32 v116, 0x4b800000, v0
	v_cmp_gt_f32_e64 s[40:41], s33, v0
	s_nop 1
	v_cndmask_b32_e64 v0, v0, v116, s[40:41]
	v_rsq_f32_e32 v0, v0
	s_nop 0
	v_mul_f32_e32 v116, 0x45800000, v0
	v_cndmask_b32_e64 v116, v0, v116, s[40:41]
	v_pk_mul_f32 v[112:113], v[112:113], v[116:117] op_sel_hi:[1,0]
	v_pk_mul_f32 v[118:119], v[110:111], v[116:117] op_sel_hi:[1,0]
	v_pk_mul_f32 v[108:109], v[108:109], v[116:117] op_sel_hi:[1,0]
	v_pk_mul_f32 v[110:111], v[106:107], v[116:117] op_sel_hi:[1,0]
	s_cbranch_vccnz .LBB0_722
	v_mul_f32_e32 v0, 0xbfb8aa3b, v118
	v_exp_f32_e32 v0, v0
	s_nop 0
	v_add_f32_e32 v0, 1.0, v0
	v_rcp_f32_e32 v106, v0
	v_mul_f32_e32 v0, 0xbfb8aa3b, v110
	v_exp_f32_e32 v0, v0
	s_nop 0
	v_add_f32_e32 v0, 1.0, v0
	v_rcp_f32_e32 v120, v0
	v_mul_f32_e32 v0, 0xbfb8aa3b, v119
	v_exp_f32_e32 v0, v0
	s_nop 0
	v_add_f32_e32 v0, 1.0, v0
	v_rcp_f32_e32 v107, v0
	v_mul_f32_e32 v0, 0xbfb8aa3b, v111
	v_exp_f32_e32 v0, v0
	v_pk_mul_f32 v[118:119], v[118:119], v[106:107]
	v_add_f32_e32 v0, 1.0, v0
	v_rcp_f32_e32 v121, v0
	v_mul_f32_e32 v0, 0xbfb8aa3b, v112
	v_exp_f32_e32 v0, v0
	v_pk_mul_f32 v[110:111], v[110:111], v[120:121]
	v_add_f32_e32 v0, 1.0, v0
	v_rcp_f32_e32 v124, v0
	v_mul_f32_e32 v0, 0xbfb8aa3b, v108
	v_exp_f32_e32 v0, v0
	s_nop 0
	v_add_f32_e32 v0, 1.0, v0
	v_rcp_f32_e32 v126, v0
	v_mul_f32_e32 v0, 0xbfb8aa3b, v113
	v_exp_f32_e32 v0, v0
	s_nop 0
	v_add_f32_e32 v0, 1.0, v0
	v_rcp_f32_e32 v125, v0
	v_mul_f32_e32 v0, 0xbfb8aa3b, v109
	v_exp_f32_e32 v0, v0
	v_pk_mul_f32 v[112:113], v[112:113], v[124:125]
	v_add_f32_e32 v0, 1.0, v0
	v_rcp_f32_e32 v127, v0
	s_nop 0
	v_pk_mul_f32 v[108:109], v[108:109], v[126:127]

; __device__ __forceinline__ u32x4 pack8(const f32x4 a, const f32x4 b) { u32x4 w; w.x = cvt_pk_bf16(a[0], a[1]); w.y = cvt_pk_bf16(a[2], a[3]); w.z = cvt_pk_bf16(b[0], b[1]); w.w = cvt_pk_bf16(b[2], b[3]); return w; }
; __device__ __forceinline__ float silu_(float v) { return v * __builtin_amdgcn_rcpf(1.0f + __expf(-v)); }
;     __device__ __forceinline__ void operator()(const f32x4 (&acc)[2][2][4][2], const Unit& u, int wr, int wc, int fr, int fq) const {
;     ...
;             for (int m = 0; m < 4; ++m) { const int row = u.pm * 256 + ai * 128 + wr * 64 + m * 16 + fr; const float rs = rsqrtf(ssq[row] * (1.0f / 1024.0f) + NEPS);
; #pragma unroll
;                 for (int bj = 0; bj < 2; ++bj) { f32x4 v0 = acc[ai][bj][m][0] * rs, v1 = acc[ai][bj][m][1] * rs;
;                     if (act) {
; #pragma unroll
;                         for (int e = 0; e < 4; ++e) { v0[e] = silu_(v0[e]); v1[e] = silu_(v1[e]); } }
;                     *(u32x4*)(dst + (size_t)row * 1024 + colt + bj * 128) = pack8(v0, v1); } }
.LBB0_724:
	v_cvt_pk_bf16_f32 v102, v102, v103
	v_cvt_pk_bf16_f32 v103, v104, v105
	v_cvt_pk_bf16_f32 v104, v98, v99
	v_add_u32_e32 v98, s12, v155
	v_cvt_pk_bf16_f32 v105, v100, v101
	v_ashrrev_i32_e32 v99, 31, v98
	global_store_dwordx4 v[106:107], v[102:105], off offset:256
	v_lshl_add_u64 v[100:101], v[98:99], 2, s[0:1]
	s_waitcnt vmcnt(9)
	v_mov_b32_e32 v0, v246
	s_and_b64 vcc, exec, s[38:39]
	v_fmamk_f32 v0, v0, 0x3a800000, v196
	v_mul_f32_e32 v100, 0x4b800000, v0
	v_cmp_gt_f32_e64 s[40:41], s33, v0
	s_nop 1
	v_cndmask_b32_e64 v0, v0, v100, s[40:41]
	v_rsq_f32_e32 v0, v0
	s_nop 0
	v_mul_f32_e32 v100, 0x45800000, v0
	v_cndmask_b32_e64 v100, v0, v100, s[40:41]
	v_pk_mul_f32 v[96:97], v[96:97], v[100:101] op_sel_hi:[1,0]
	v_pk_mul_f32 v[102:103], v[94:95], v[100:101] op_sel_hi:[1,0]
	v_pk_mul_f32 v[92:93], v[92:93], v[100:101] op_sel_hi:[1,0]
	v_pk_mul_f32 v[94:95], v[90:91], v[100:101] op_sel_hi:[1,0]
	s_cbranch_vccnz .LBB0_726
	v_mul_f32_e32 v0, 0xbfb8aa3b, v102
	v_exp_f32_e32 v0, v0
	s_nop 0
	v_add_f32_e32 v0, 1.0, v0
	v_rcp_f32_e32 v90, v0
	v_mul_f32_e32 v0, 0xbfb8aa3b, v94
	v_exp_f32_e32 v0, v0
	s_nop 0
	v_add_f32_e32 v0, 1.0, v0
	v_rcp_f32_e32 v104, v0
	v_mul_f32_e32 v0, 0xbfb8aa3b, v103
	v_exp_f32_e32 v0, v0
	s_nop 0
	v_add_f32_e32 v0, 1.0, v0
	v_rcp_f32_e32 v91, v0
	v_mul_f32_e32 v0, 0xbfb8aa3b, v95
	v_exp_f32_e32 v0, v0
	v_pk_mul_f32 v[102:103], v[102:103], v[90:91]
	v_add_f32_e32 v0, 1.0, v0
	v_rcp_f32_e32 v105, v0
	v_mul_f32_e32 v0, 0xbfb8aa3b, v96
	v_exp_f32_e32 v0, v0
	v_pk_mul_f32 v[94:95], v[94:95], v[104:105]
	v_add_f32_e32 v0, 1.0, v0
	v_rcp_f32_e32 v106, v0
	v_mul_f32_e32 v0, 0xbfb8aa3b, v92
	v_exp_f32_e32 v0, v0
	s_nop 0
	v_add_f32_e32 v0, 1.0, v0
	v_rcp_f32_e32 v108, v0
	v_mul_f32_e32 v0, 0xbfb8aa3b, v97
	v_exp_f32_e32 v0, v0
	s_nop 0
	v_add_f32_e32 v0, 1.0, v0
	v_rcp_f32_e32 v107, v0
	v_mul_f32_e32 v0, 0xbfb8aa3b, v93
	v_exp_f32_e32 v0, v0
	v_pk_mul_f32 v[96:97], v[96:97], v[106:107]
	v_add_f32_e32 v0, 1.0, v0
	v_rcp_f32_e32 v109, v0
	s_nop 0
	v_pk_mul_f32 v[92:93], v[92:93], v[108:109]

; __device__ __forceinline__ u32x4 pack8(const f32x4 a, const f32x4 b) { u32x4 w; w.x = cvt_pk_bf16(a[0], a[1]); w.y = cvt_pk_bf16(a[2], a[3]); w.z = cvt_pk_bf16(b[0], b[1]); w.w = cvt_pk_bf16(b[2], b[3]); return w; }
; __device__ __forceinline__ float silu_(float v) { return v * __builtin_amdgcn_rcpf(1.0f + __expf(-v)); }
;     __device__ __forceinline__ void operator()(const f32x4 (&acc)[2][2][4][2], const Unit& u, int wr, int wc, int fr, int fq) const {
;     ...
;             for (int m = 0; m < 4; ++m) { const int row = u.pm * 256 + ai * 128 + wr * 64 + m * 16 + fr; const float rs = rsqrtf(ssq[row] * (1.0f / 1024.0f) + NEPS);
; #pragma unroll
;                 for (int bj = 0; bj < 2; ++bj) { f32x4 v0 = acc[ai][bj][m][0] * rs, v1 = acc[ai][bj][m][1] * rs;
;                     if (act) {
; #pragma unroll
;                         for (int e = 0; e < 4; ++e) { v0[e] = silu_(v0[e]); v1[e] = silu_(v1[e]); } }
;                     *(u32x4*)(dst + (size_t)row * 1024 + colt + bj * 128) = pack8(v0, v1); } }
.LBB0_728:
	v_cvt_pk_bf16_f32 v86, v86, v87
	v_cvt_pk_bf16_f32 v87, v88, v89
	v_cvt_pk_bf16_f32 v88, v82, v83
	v_add_u32_e32 v82, s12, v156
	v_cvt_pk_bf16_f32 v89, v84, v85
	v_ashrrev_i32_e32 v83, 31, v82
	global_store_dwordx4 v[90:91], v[86:89], off offset:256
	v_lshl_add_u64 v[84:85], v[82:83], 2, s[0:1]
	s_waitcnt vmcnt(10)
	v_mov_b32_e32 v0, v247
	s_and_b64 vcc, exec, s[38:39]
	v_fmamk_f32 v0, v0, 0x3a800000, v196
	v_mul_f32_e32 v84, 0x4b800000, v0
	v_cmp_gt_f32_e64 s[40:41], s33, v0
	s_nop 1
	v_cndmask_b32_e64 v0, v0, v84, s[40:41]
	v_rsq_f32_e32 v0, v0
	s_nop 0
	v_mul_f32_e32 v84, 0x45800000, v0
	v_cndmask_b32_e64 v84, v0, v84, s[40:41]
	v_pk_mul_f32 v[80:81], v[80:81], v[84:85] op_sel_hi:[1,0]
	v_pk_mul_f32 v[86:87], v[78:79], v[84:85] op_sel_hi:[1,0]
	v_pk_mul_f32 v[76:77], v[76:77], v[84:85] op_sel_hi:[1,0]
	v_pk_mul_f32 v[78:79], v[74:75], v[84:85] op_sel_hi:[1,0]
	s_cbranch_vccnz .LBB0_730
	v_mul_f32_e32 v0, 0xbfb8aa3b, v86
	v_exp_f32_e32 v0, v0
	s_nop 0
	v_add_f32_e32 v0, 1.0, v0
	v_rcp_f32_e32 v74, v0
	v_mul_f32_e32 v0, 0xbfb8aa3b, v78
	v_exp_f32_e32 v0, v0
	s_nop 0
	v_add_f32_e32 v0, 1.0, v0
	v_rcp_f32_e32 v88, v0
	v_mul_f32_e32 v0, 0xbfb8aa3b, v87
	v_exp_f32_e32 v0, v0
	s_nop 0
	v_add_f32_e32 v0, 1.0, v0
	v_rcp_f32_e32 v75, v0
	v_mul_f32_e32 v0, 0xbfb8aa3b, v79
	v_exp_f32_e32 v0, v0
	v_pk_mul_f32 v[86:87], v[86:87], v[74:75]
	v_add_f32_e32 v0, 1.0, v0
	v_rcp_f32_e32 v89, v0
	v_mul_f32_e32 v0, 0xbfb8aa3b, v80
	v_exp_f32_e32 v0, v0
	v_pk_mul_f32 v[78:79], v[78:79], v[88:89]
	v_add_f32_e32 v0, 1.0, v0
	v_rcp_f32_e32 v90, v0
	v_mul_f32_e32 v0, 0xbfb8aa3b, v76
	v_exp_f32_e32 v0, v0
	s_nop 0
	v_add_f32_e32 v0, 1.0, v0
	v_rcp_f32_e32 v92, v0
	v_mul_f32_e32 v0, 0xbfb8aa3b, v81
	v_exp_f32_e32 v0, v0
	s_nop 0
	v_add_f32_e32 v0, 1.0, v0
	v_rcp_f32_e32 v91, v0
	v_mul_f32_e32 v0, 0xbfb8aa3b, v77
	v_exp_f32_e32 v0, v0
	v_pk_mul_f32 v[80:81], v[80:81], v[90:91]
	v_add_f32_e32 v0, 1.0, v0
	v_rcp_f32_e32 v93, v0
	s_nop 0
	v_pk_mul_f32 v[76:77], v[76:77], v[92:93]

; __device__ __forceinline__ u32x4 pack8(const f32x4 a, const f32x4 b) { u32x4 w; w.x = cvt_pk_bf16(a[0], a[1]); w.y = cvt_pk_bf16(a[2], a[3]); w.z = cvt_pk_bf16(b[0], b[1]); w.w = cvt_pk_bf16(b[2], b[3]); return w; }
; __device__ __forceinline__ float silu_(float v) { return v * __builtin_amdgcn_rcpf(1.0f + __expf(-v)); }
;     __device__ __forceinline__ void operator()(const f32x4 (&acc)[2][2][4][2], const Unit& u, int wr, int wc, int fr, int fq) const {
;     ...
;             for (int m = 0; m < 4; ++m) { const int row = u.pm * 256 + ai * 128 + wr * 64 + m * 16 + fr; const float rs = rsqrtf(ssq[row] * (1.0f / 1024.0f) + NEPS);
; #pragma unroll
;                 for (int bj = 0; bj < 2; ++bj) { f32x4 v0 = acc[ai][bj][m][0] * rs, v1 = acc[ai][bj][m][1] * rs;
;                     if (act) {
; #pragma unroll
;                         for (int e = 0; e < 4; ++e) { v0[e] = silu_(v0[e]); v1[e] = silu_(v1[e]); } }
;                     *(u32x4*)(dst + (size_t)row * 1024 + colt + bj * 128) = pack8(v0, v1); } }
.LBB0_732:
	v_cvt_pk_bf16_f32 v70, v70, v71
	v_cvt_pk_bf16_f32 v71, v72, v73
	v_cvt_pk_bf16_f32 v72, v66, v67
	v_add_u32_e32 v66, 0x80, v142
	v_cvt_pk_bf16_f32 v73, v68, v69
	v_ashrrev_i32_e32 v67, 31, v66
	global_store_dwordx4 v[74:75], v[70:73], off offset:256
	v_lshl_add_u64 v[68:69], v[66:67], 2, s[0:1]
	s_waitcnt vmcnt(11)
	v_mov_b32_e32 v0, v248
	s_and_b64 vcc, exec, s[38:39]
	v_fmamk_f32 v0, v0, 0x3a800000, v196
	v_mul_f32_e32 v68, 0x4b800000, v0
	v_cmp_gt_f32_e64 s[40:41], s33, v0
	s_nop 1
	v_cndmask_b32_e64 v0, v0, v68, s[40:41]
	v_rsq_f32_e32 v0, v0
	s_nop 0
	v_mul_f32_e32 v68, 0x45800000, v0
	v_cndmask_b32_e64 v68, v0, v68, s[40:41]
	v_pk_mul_f32 v[64:65], v[64:65], v[68:69] op_sel_hi:[1,0]
	v_pk_mul_f32 v[70:71], v[62:63], v[68:69] op_sel_hi:[1,0]
	v_pk_mul_f32 v[60:61], v[60:61], v[68:69] op_sel_hi:[1,0]
	v_pk_mul_f32 v[62:63], v[58:59], v[68:69] op_sel_hi:[1,0]
	s_cbranch_vccnz .LBB0_734
	v_mul_f32_e32 v0, 0xbfb8aa3b, v70
	v_exp_f32_e32 v0, v0
	s_nop 0
	v_add_f32_e32 v0, 1.0, v0
	v_rcp_f32_e32 v58, v0
	v_mul_f32_e32 v0, 0xbfb8aa3b, v62
	v_exp_f32_e32 v0, v0
	s_nop 0
	v_add_f32_e32 v0, 1.0, v0
	v_rcp_f32_e32 v72, v0
	v_mul_f32_e32 v0, 0xbfb8aa3b, v71
	v_exp_f32_e32 v0, v0
	s_nop 0
	v_add_f32_e32 v0, 1.0, v0
	v_rcp_f32_e32 v59, v0
	v_mul_f32_e32 v0, 0xbfb8aa3b, v63
	v_exp_f32_e32 v0, v0
	v_pk_mul_f32 v[70:71], v[70:71], v[58:59]
	v_add_f32_e32 v0, 1.0, v0
	v_rcp_f32_e32 v73, v0
	v_mul_f32_e32 v0, 0xbfb8aa3b, v64
	v_exp_f32_e32 v0, v0
	v_pk_mul_f32 v[62:63], v[62:63], v[72:73]
	v_add_f32_e32 v0, 1.0, v0
	v_rcp_f32_e32 v74, v0
	v_mul_f32_e32 v0, 0xbfb8aa3b, v60
	v_exp_f32_e32 v0, v0
	s_nop 0
	v_add_f32_e32 v0, 1.0, v0
	v_rcp_f32_e32 v76, v0
	v_mul_f32_e32 v0, 0xbfb8aa3b, v65
	v_exp_f32_e32 v0, v0
	s_nop 0
	v_add_f32_e32 v0, 1.0, v0
	v_rcp_f32_e32 v75, v0
	v_mul_f32_e32 v0, 0xbfb8aa3b, v61
	v_exp_f32_e32 v0, v0
	v_pk_mul_f32 v[64:65], v[64:65], v[74:75]
	v_add_f32_e32 v0, 1.0, v0
	v_rcp_f32_e32 v77, v0
	s_nop 0
	v_pk_mul_f32 v[60:61], v[60:61], v[76:77]

; __device__ __forceinline__ u32x4 pack8(const f32x4 a, const f32x4 b) { u32x4 w; w.x = cvt_pk_bf16(a[0], a[1]); w.y = cvt_pk_bf16(a[2], a[3]); w.z = cvt_pk_bf16(b[0], b[1]); w.w = cvt_pk_bf16(b[2], b[3]); return w; }
; __device__ __forceinline__ float silu_(float v) { return v * __builtin_amdgcn_rcpf(1.0f + __expf(-v)); }
;     __device__ __forceinline__ void operator()(const f32x4 (&acc)[2][2][4][2], const Unit& u, int wr, int wc, int fr, int fq) const {
;     ...
;             for (int m = 0; m < 4; ++m) { const int row = u.pm * 256 + ai * 128 + wr * 64 + m * 16 + fr; const float rs = rsqrtf(ssq[row] * (1.0f / 1024.0f) + NEPS);
; #pragma unroll
;                 for (int bj = 0; bj < 2; ++bj) { f32x4 v0 = acc[ai][bj][m][0] * rs, v1 = acc[ai][bj][m][1] * rs;
;                     if (act) {
; #pragma unroll
;                         for (int e = 0; e < 4; ++e) { v0[e] = silu_(v0[e]); v1[e] = silu_(v1[e]); } }
;                     *(u32x4*)(dst + (size_t)row * 1024 + colt + bj * 128) = pack8(v0, v1); } }
.LBB0_736:
	v_cvt_pk_bf16_f32 v54, v54, v55
	v_cvt_pk_bf16_f32 v55, v56, v57
	v_cvt_pk_bf16_f32 v56, v50, v51
	v_add_u32_e32 v50, 0x90, v142
	v_cvt_pk_bf16_f32 v57, v52, v53
	v_ashrrev_i32_e32 v51, 31, v50
	global_store_dwordx4 v[58:59], v[54:57], off offset:256
	v_lshl_add_u64 v[52:53], v[50:51], 2, s[0:1]
	s_waitcnt vmcnt(12)
	v_mov_b32_e32 v0, v249
	s_and_b64 vcc, exec, s[38:39]
	v_fmamk_f32 v0, v0, 0x3a800000, v196
	v_mul_f32_e32 v52, 0x4b800000, v0
	v_cmp_gt_f32_e64 s[40:41], s33, v0
	s_nop 1
	v_cndmask_b32_e64 v0, v0, v52, s[40:41]
	v_rsq_f32_e32 v0, v0
	s_nop 0
	v_mul_f32_e32 v52, 0x45800000, v0
	v_cndmask_b32_e64 v52, v0, v52, s[40:41]
	v_pk_mul_f32 v[48:49], v[48:49], v[52:53] op_sel_hi:[1,0]
	v_pk_mul_f32 v[54:55], v[46:47], v[52:53] op_sel_hi:[1,0]
	v_pk_mul_f32 v[44:45], v[44:45], v[52:53] op_sel_hi:[1,0]
	v_pk_mul_f32 v[46:47], v[42:43], v[52:53] op_sel_hi:[1,0]
	s_cbranch_vccnz .LBB0_738
	v_mul_f32_e32 v0, 0xbfb8aa3b, v54
	v_exp_f32_e32 v0, v0
	s_nop 0
	v_add_f32_e32 v0, 1.0, v0
	v_rcp_f32_e32 v42, v0
	v_mul_f32_e32 v0, 0xbfb8aa3b, v46
	v_exp_f32_e32 v0, v0
	s_nop 0
	v_add_f32_e32 v0, 1.0, v0
	v_rcp_f32_e32 v56, v0
	v_mul_f32_e32 v0, 0xbfb8aa3b, v55
	v_exp_f32_e32 v0, v0
	s_nop 0
	v_add_f32_e32 v0, 1.0, v0
	v_rcp_f32_e32 v43, v0
	v_mul_f32_e32 v0, 0xbfb8aa3b, v47
	v_exp_f32_e32 v0, v0
	v_pk_mul_f32 v[54:55], v[54:55], v[42:43]
	v_add_f32_e32 v0, 1.0, v0
	v_rcp_f32_e32 v57, v0
	v_mul_f32_e32 v0, 0xbfb8aa3b, v48
	v_exp_f32_e32 v0, v0
	v_pk_mul_f32 v[46:47], v[46:47], v[56:57]
	v_add_f32_e32 v0, 1.0, v0
	v_rcp_f32_e32 v58, v0
	v_mul_f32_e32 v0, 0xbfb8aa3b, v44
	v_exp_f32_e32 v0, v0
	s_nop 0
	v_add_f32_e32 v0, 1.0, v0
	v_rcp_f32_e32 v60, v0
	v_mul_f32_e32 v0, 0xbfb8aa3b, v49
	v_exp_f32_e32 v0, v0
	s_nop 0
	v_add_f32_e32 v0, 1.0, v0
	v_rcp_f32_e32 v59, v0
	v_mul_f32_e32 v0, 0xbfb8aa3b, v45
	v_exp_f32_e32 v0, v0
	v_pk_mul_f32 v[48:49], v[48:49], v[58:59]
	v_add_f32_e32 v0, 1.0, v0
	v_rcp_f32_e32 v61, v0
	s_nop 0
	v_pk_mul_f32 v[44:45], v[44:45], v[60:61]

; __device__ __forceinline__ u32x4 pack8(const f32x4 a, const f32x4 b) { u32x4 w; w.x = cvt_pk_bf16(a[0], a[1]); w.y = cvt_pk_bf16(a[2], a[3]); w.z = cvt_pk_bf16(b[0], b[1]); w.w = cvt_pk_bf16(b[2], b[3]); return w; }
; __device__ __forceinline__ float silu_(float v) { return v * __builtin_amdgcn_rcpf(1.0f + __expf(-v)); }
;     __device__ __forceinline__ void operator()(const f32x4 (&acc)[2][2][4][2], const Unit& u, int wr, int wc, int fr, int fq) const {
;     ...
;             for (int m = 0; m < 4; ++m) { const int row = u.pm * 256 + ai * 128 + wr * 64 + m * 16 + fr; const float rs = rsqrtf(ssq[row] * (1.0f / 1024.0f) + NEPS);
; #pragma unroll
;                 for (int bj = 0; bj < 2; ++bj) { f32x4 v0 = acc[ai][bj][m][0] * rs, v1 = acc[ai][bj][m][1] * rs;
;                     if (act) {
; #pragma unroll
;                         for (int e = 0; e < 4; ++e) { v0[e] = silu_(v0[e]); v1[e] = silu_(v1[e]); } }
;                     *(u32x4*)(dst + (size_t)row * 1024 + colt + bj * 128) = pack8(v0, v1); } }
.LBB0_740:
	v_cvt_pk_bf16_f32 v38, v38, v39
	v_cvt_pk_bf16_f32 v39, v40, v41
	v_cvt_pk_bf16_f32 v40, v34, v35
	v_add_u32_e32 v34, 0xa0, v142
	v_cvt_pk_bf16_f32 v41, v36, v37
	v_ashrrev_i32_e32 v35, 31, v34
	global_store_dwordx4 v[42:43], v[38:41], off offset:256
	v_lshl_add_u64 v[36:37], v[34:35], 2, s[0:1]
	s_waitcnt vmcnt(13)
	v_mov_b32_e32 v0, v250
	s_and_b64 vcc, exec, s[38:39]
	v_fmamk_f32 v0, v0, 0x3a800000, v196
	v_mul_f32_e32 v36, 0x4b800000, v0
	v_cmp_gt_f32_e64 s[40:41], s33, v0
	s_nop 1
	v_cndmask_b32_e64 v0, v0, v36, s[40:41]
	v_rsq_f32_e32 v0, v0
	s_nop 0
	v_mul_f32_e32 v36, 0x45800000, v0
	v_cndmask_b32_e64 v36, v0, v36, s[40:41]
	v_pk_mul_f32 v[32:33], v[32:33], v[36:37] op_sel_hi:[1,0]
	v_pk_mul_f32 v[38:39], v[30:31], v[36:37] op_sel_hi:[1,0]
	v_pk_mul_f32 v[28:29], v[28:29], v[36:37] op_sel_hi:[1,0]
	v_pk_mul_f32 v[30:31], v[26:27], v[36:37] op_sel_hi:[1,0]
	s_cbranch_vccnz .LBB0_742
	v_mul_f32_e32 v0, 0xbfb8aa3b, v38
	v_exp_f32_e32 v0, v0
	s_nop 0
	v_add_f32_e32 v0, 1.0, v0
	v_rcp_f32_e32 v26, v0
	v_mul_f32_e32 v0, 0xbfb8aa3b, v30
	v_exp_f32_e32 v0, v0
	s_nop 0
	v_add_f32_e32 v0, 1.0, v0
	v_rcp_f32_e32 v40, v0
	v_mul_f32_e32 v0, 0xbfb8aa3b, v39
	v_exp_f32_e32 v0, v0
	s_nop 0
	v_add_f32_e32 v0, 1.0, v0
	v_rcp_f32_e32 v27, v0
	v_mul_f32_e32 v0, 0xbfb8aa3b, v31
	v_exp_f32_e32 v0, v0
	v_pk_mul_f32 v[38:39], v[38:39], v[26:27]
	v_add_f32_e32 v0, 1.0, v0
	v_rcp_f32_e32 v41, v0
	v_mul_f32_e32 v0, 0xbfb8aa3b, v32
	v_exp_f32_e32 v0, v0
	v_pk_mul_f32 v[30:31], v[30:31], v[40:41]
	v_add_f32_e32 v0, 1.0, v0
	v_rcp_f32_e32 v42, v0
	v_mul_f32_e32 v0, 0xbfb8aa3b, v28
	v_exp_f32_e32 v0, v0
	s_nop 0
	v_add_f32_e32 v0, 1.0, v0
	v_rcp_f32_e32 v44, v0
	v_mul_f32_e32 v0, 0xbfb8aa3b, v33
	v_exp_f32_e32 v0, v0
	s_nop 0
	v_add_f32_e32 v0, 1.0, v0
	v_rcp_f32_e32 v43, v0
	v_mul_f32_e32 v0, 0xbfb8aa3b, v29
	v_exp_f32_e32 v0, v0
	v_pk_mul_f32 v[32:33], v[32:33], v[42:43]
	v_add_f32_e32 v0, 1.0, v0
	v_rcp_f32_e32 v45, v0
	s_nop 0
	v_pk_mul_f32 v[28:29], v[28:29], v[44:45]

; __device__ __forceinline__ u32x4 pack8(const f32x4 a, const f32x4 b) { u32x4 w; w.x = cvt_pk_bf16(a[0], a[1]); w.y = cvt_pk_bf16(a[2], a[3]); w.z = cvt_pk_bf16(b[0], b[1]); w.w = cvt_pk_bf16(b[2], b[3]); return w; }
; __device__ __forceinline__ float silu_(float v) { return v * __builtin_amdgcn_rcpf(1.0f + __expf(-v)); }
;     __device__ __forceinline__ void operator()(const f32x4 (&acc)[2][2][4][2], const Unit& u, int wr, int wc, int fr, int fq) const {
;     ...
;             for (int m = 0; m < 4; ++m) { const int row = u.pm * 256 + ai * 128 + wr * 64 + m * 16 + fr; const float rs = rsqrtf(ssq[row] * (1.0f / 1024.0f) + NEPS);
; #pragma unroll
;                 for (int bj = 0; bj < 2; ++bj) { f32x4 v0 = acc[ai][bj][m][0] * rs, v1 = acc[ai][bj][m][1] * rs;
;                     if (act) {
; #pragma unroll
;                         for (int e = 0; e < 4; ++e) { v0[e] = silu_(v0[e]); v1[e] = silu_(v1[e]); } }
;                     *(u32x4*)(dst + (size_t)row * 1024 + colt + bj * 128) = pack8(v0, v1); } }
.LBB0_744:
	v_cvt_pk_bf16_f32 v22, v22, v23
	v_cvt_pk_bf16_f32 v23, v24, v25
	v_cvt_pk_bf16_f32 v24, v18, v19
	v_add_u32_e32 v18, 0xb0, v142
	v_cvt_pk_bf16_f32 v25, v20, v21
	v_ashrrev_i32_e32 v19, 31, v18
	global_store_dwordx4 v[26:27], v[22:25], off offset:256
	v_lshl_add_u64 v[20:21], v[18:19], 2, s[0:1]
	s_waitcnt vmcnt(14)
	v_mov_b32_e32 v0, v251
	s_and_b64 vcc, exec, s[38:39]
	v_fmamk_f32 v0, v0, 0x3a800000, v196
	v_mul_f32_e32 v20, 0x4b800000, v0
	v_cmp_gt_f32_e64 s[40:41], s33, v0
	s_nop 1
	v_cndmask_b32_e64 v0, v0, v20, s[40:41]
	v_rsq_f32_e32 v0, v0
	s_nop 0
	v_mul_f32_e32 v20, 0x45800000, v0
	v_cndmask_b32_e64 v20, v0, v20, s[40:41]
	v_pk_mul_f32 v[16:17], v[16:17], v[20:21] op_sel_hi:[1,0]
	v_pk_mul_f32 v[22:23], v[14:15], v[20:21] op_sel_hi:[1,0]
	v_pk_mul_f32 v[12:13], v[12:13], v[20:21] op_sel_hi:[1,0]
	v_pk_mul_f32 v[14:15], v[10:11], v[20:21] op_sel_hi:[1,0]
	s_cbranch_vccnz .LBB0_746
	v_mul_f32_e32 v0, 0xbfb8aa3b, v22
	v_exp_f32_e32 v0, v0
	s_nop 0
	v_add_f32_e32 v0, 1.0, v0
	v_rcp_f32_e32 v10, v0
	v_mul_f32_e32 v0, 0xbfb8aa3b, v14
	v_exp_f32_e32 v0, v0
	s_nop 0
	v_add_f32_e32 v0, 1.0, v0
	v_rcp_f32_e32 v24, v0
	v_mul_f32_e32 v0, 0xbfb8aa3b, v23
	v_exp_f32_e32 v0, v0
	s_nop 0
	v_add_f32_e32 v0, 1.0, v0
	v_rcp_f32_e32 v11, v0
	v_mul_f32_e32 v0, 0xbfb8aa3b, v15
	v_exp_f32_e32 v0, v0
	v_pk_mul_f32 v[22:23], v[22:23], v[10:11]
	v_add_f32_e32 v0, 1.0, v0
	v_rcp_f32_e32 v25, v0
	v_mul_f32_e32 v0, 0xbfb8aa3b, v16
	v_exp_f32_e32 v0, v0
	v_pk_mul_f32 v[14:15], v[14:15], v[24:25]
	v_add_f32_e32 v0, 1.0, v0
	v_rcp_f32_e32 v26, v0
	v_mul_f32_e32 v0, 0xbfb8aa3b, v12
	v_exp_f32_e32 v0, v0
	s_nop 0
	v_add_f32_e32 v0, 1.0, v0
	v_rcp_f32_e32 v28, v0
	v_mul_f32_e32 v0, 0xbfb8aa3b, v17
	v_exp_f32_e32 v0, v0
	s_nop 0
	v_add_f32_e32 v0, 1.0, v0
	v_rcp_f32_e32 v27, v0
	v_mul_f32_e32 v0, 0xbfb8aa3b, v13
	v_exp_f32_e32 v0, v0
	v_pk_mul_f32 v[16:17], v[16:17], v[26:27]
	v_add_f32_e32 v0, 1.0, v0
	v_rcp_f32_e32 v29, v0
	s_nop 0
	v_pk_mul_f32 v[12:13], v[12:13], v[28:29]
